# stack6 + up epilogue: the 64 row-shift DPP copies folded into the conv FMAs that consume them (48 packed FMAs become 96 v_fmac_f32_dpp reading the unshifted rows; same products, same accumulation orde
# speedup vs baseline: 1.0042x; 1.0035x over previous
.LBB0_738:
	s_or_b64 exec, exec, s[0:1]
	s_mov_b32 s0, 0
	v_pk_fma_f32 v[46:47], v[142:143], v[186:187], v[146:147]
	v_pk_fma_f32 v[48:49], v[182:183], v[162:163], v[166:167]
	v_pk_fma_f32 v[198:199], v[184:185], v[164:165], v[168:169]
	v_pk_fma_f32 v[46:47], v[126:127], v[170:171], v[46:47]
	v_pk_fma_f32 v[48:49], v[114:115], v[178:179], v[48:49]
	v_pk_fma_f32 v[198:199], v[116:117], v[180:181], v[198:199]
	v_pk_fma_f32 v[46:47], v[122:123], v[158:159], v[46:47]
	v_pk_fma_f32 v[48:49], v[110:111], v[194:195], v[48:49]
	v_pk_fma_f32 v[200:201], v[170:171], v[142:143], v[146:147]
	v_pk_mul_f32 v[202:203], v[46:47], s[82:83] op_sel_hi:[1,0]
	v_pk_fma_f32 v[198:199], v[112:113], v[196:197], v[198:199]
	v_pk_fma_f32 v[200:201], v[126:127], v[158:159], v[200:201]
	v_exp_f32_e32 v204, v202
	v_exp_f32_e32 v205, v203
	v_pk_fma_f32 v[200:201], v[122:123], v[154:155], v[200:201]
	v_pk_fma_f32 v[202:203], v[180:181], v[164:165], v[168:169]
	v_pk_fma_f32 v[206:207], v[178:179], v[162:163], v[166:167]
	v_pk_add_f32 v[204:205], v[204:205], 1.0 op_sel_hi:[1,0]
	v_pk_fma_f32 v[202:203], v[196:197], v[116:117], v[202:203]
	v_pk_fma_f32 v[206:207], v[194:195], v[114:115], v[206:207]
	v_pk_fma_f32 v[196:197], v[196:197], v[164:165], v[168:169]
	v_pk_fma_f32 v[202:203], v[112:113], v[192:193], v[202:203]
	v_pk_fma_f32 v[206:207], v[110:111], v[190:191], v[206:207]
	v_pk_fma_f32 v[158:159], v[158:159], v[142:143], v[146:147]
	v_pk_fma_f32 v[194:195], v[194:195], v[162:163], v[166:167]
	v_pk_fma_f32 v[158:159], v[154:155], v[126:127], v[158:159]
	v_pk_fma_f32 v[154:155], v[154:155], v[142:143], v[146:147]
	v_pk_fma_f32 v[196:197], v[192:193], v[116:117], v[196:197]
	v_fmac_f32_dpp v158, v186, v122 row_shr:1 row_mask:0xf bank_mask:0xf bound_ctrl:1
	v_fmac_f32_dpp v159, v187, v123 row_shr:1 row_mask:0xf bank_mask:0xf bound_ctrl:1
	v_fmac_f32_dpp v154, v186, v126 row_shr:1 row_mask:0xf bank_mask:0xf bound_ctrl:1
	v_fmac_f32_dpp v155, v187, v127 row_shr:1 row_mask:0xf bank_mask:0xf bound_ctrl:1
	v_rcp_f32_e32 v186, v204
	v_rcp_f32_e32 v187, v205
	v_pk_mul_f32 v[204:205], v[200:201], s[82:83] op_sel_hi:[1,0]
	v_fmac_f32_dpp v154, v170, v122 row_shr:1 row_mask:0xf bank_mask:0xf bound_ctrl:1
	v_fmac_f32_dpp v155, v171, v123 row_shr:1 row_mask:0xf bank_mask:0xf bound_ctrl:1
	v_pk_fma_f32 v[170:171], v[190:191], v[114:115], v[194:195]
	v_pk_mul_f32 v[46:47], v[46:47], v[186:187]
	v_exp_f32_e32 v186, v204
	v_exp_f32_e32 v187, v205
	v_pk_mul_f32 v[46:47], v[48:49], v[46:47]
	v_pk_mul_f32 v[48:49], v[154:155], s[82:83] op_sel_hi:[1,0]
	v_pk_fma_f32 v[190:191], v[190:191], v[162:163], v[166:167]
	v_pk_add_f32 v[186:187], v[186:187], 1.0 op_sel_hi:[1,0]
	v_exp_f32_e32 v194, v48
	v_exp_f32_e32 v195, v49
	v_rcp_f32_e32 v48, v186
	v_rcp_f32_e32 v49, v187
	v_fmac_f32_dpp v190, v182, v114 row_shr:1 row_mask:0xf bank_mask:0xf bound_ctrl:1
	v_fmac_f32_dpp v191, v183, v115 row_shr:1 row_mask:0xf bank_mask:0xf bound_ctrl:1
	v_pk_add_f32 v[186:187], v[194:195], 1.0 op_sel_hi:[1,0]
	v_fmac_f32_dpp v190, v178, v110 row_shr:1 row_mask:0xf bank_mask:0xf bound_ctrl:1
	v_pk_mul_f32 v[48:49], v[200:201], v[48:49]
	v_fmac_f32_dpp v191, v179, v111 row_shr:1 row_mask:0xf bank_mask:0xf bound_ctrl:1
	v_rcp_f32_e32 v178, v186
	v_pk_mul_f32 v[48:49], v[206:207], v[48:49]
	v_rcp_f32_e32 v179, v187
	v_pk_mul_f32 v[186:187], v[158:159], s[82:83] op_sel_hi:[1,0]
	v_fmac_f32_dpp v170, v182, v110 row_shr:1 row_mask:0xf bank_mask:0xf bound_ctrl:1
	v_fmac_f32_dpp v171, v183, v111 row_shr:1 row_mask:0xf bank_mask:0xf bound_ctrl:1
	v_pk_mul_f32 v[154:155], v[154:155], v[178:179]
	v_exp_f32_e32 v178, v186
	v_exp_f32_e32 v179, v187
	v_pk_mul_f32 v[154:155], v[190:191], v[154:155]
	v_pk_add_f32 v[178:179], v[178:179], 1.0 op_sel_hi:[1,0]
	v_rcp_f32_e32 v182, v178
	v_rcp_f32_e32 v183, v179
	v_pk_fma_f32 v[178:179], v[192:193], v[164:165], v[168:169]
	v_pk_mul_f32 v[158:159], v[158:159], v[182:183]
	v_pk_mul_f32 v[158:159], v[170:171], v[158:159]
	v_pk_fma_f32 v[170:171], v[172:173], v[144:145], v[148:149]
	v_pk_fma_f32 v[182:183], v[144:145], v[188:189], v[148:149]
	v_fmac_f32_dpp v196, v184, v112 row_shr:1 row_mask:0xf bank_mask:0xf bound_ctrl:1
	v_pk_fma_f32 v[170:171], v[128:129], v[160:161], v[170:171]
	v_pk_fma_f32 v[182:183], v[128:129], v[172:173], v[182:183]
	v_fmac_f32_dpp v197, v185, v113 row_shr:1 row_mask:0xf bank_mask:0xf bound_ctrl:1
	v_pk_fma_f32 v[170:171], v[124:125], v[156:157], v[170:171]
	v_pk_fma_f32 v[182:183], v[124:125], v[160:161], v[182:183]
	v_fmac_f32_dpp v178, v184, v116 row_shr:1 row_mask:0xf bank_mask:0xf bound_ctrl:1
	v_pk_mul_f32 v[186:187], v[170:171], s[82:83] op_sel_hi:[1,0]
	v_pk_mul_f32 v[190:191], v[182:183], s[82:83] op_sel_hi:[1,0]
	v_fmac_f32_dpp v179, v185, v117 row_shr:1 row_mask:0xf bank_mask:0xf bound_ctrl:1
	v_exp_f32_e32 v192, v186
	v_exp_f32_e32 v193, v187
	v_exp_f32_e32 v186, v190
	v_exp_f32_e32 v187, v191
	v_fmac_f32_dpp v178, v180, v112 row_shr:1 row_mask:0xf bank_mask:0xf bound_ctrl:1
	v_fmac_f32_dpp v179, v181, v113 row_shr:1 row_mask:0xf bank_mask:0xf bound_ctrl:1
	v_pk_add_f32 v[190:191], v[192:193], 1.0 op_sel_hi:[1,0]
	v_pk_fma_f32 v[192:193], v[160:161], v[144:145], v[148:149]
	v_pk_add_f32 v[186:187], v[186:187], 1.0 op_sel_hi:[1,0]
	v_rcp_f32_e32 v194, v190
	v_rcp_f32_e32 v195, v191
	v_rcp_f32_e32 v190, v186
	v_rcp_f32_e32 v191, v187
	v_pk_fma_f32 v[186:187], v[156:157], v[144:145], v[148:149]
	v_pk_mul_f32 v[170:171], v[170:171], v[194:195]
	v_pk_fma_f32 v[192:193], v[156:157], v[128:129], v[192:193]
	v_pk_mul_f32 v[182:183], v[182:183], v[190:191]
	v_fmac_f32_dpp v186, v188, v128 row_shr:1 row_mask:0xf bank_mask:0xf bound_ctrl:1
	v_fmac_f32_dpp v192, v188, v124 row_shr:1 row_mask:0xf bank_mask:0xf bound_ctrl:1
	v_fmac_f32_dpp v193, v189, v125 row_shr:1 row_mask:0xf bank_mask:0xf bound_ctrl:1
	v_fmac_f32_dpp v187, v189, v129 row_shr:1 row_mask:0xf bank_mask:0xf bound_ctrl:1
	v_fmac_f32_dpp v186, v172, v124 row_shr:1 row_mask:0xf bank_mask:0xf bound_ctrl:1
	v_pk_mul_f32 v[190:191], v[192:193], s[82:83] op_sel_hi:[1,0]
	v_fmac_f32_dpp v187, v173, v125 row_shr:1 row_mask:0xf bank_mask:0xf bound_ctrl:1
	v_exp_f32_e32 v194, v190
	v_exp_f32_e32 v195, v191
	v_pk_mul_f32 v[190:191], v[186:187], s[82:83] op_sel_hi:[1,0]
	v_exp_f32_e32 v200, v190
	v_pk_add_f32 v[194:195], v[194:195], 1.0 op_sel_hi:[1,0]
	v_exp_f32_e32 v201, v191
	v_pk_fma_f32 v[190:191], v[102:103], v[26:27], v[30:31]
	v_rcp_f32_e32 v204, v194
	v_rcp_f32_e32 v205, v195
	v_pk_add_f32 v[194:195], v[200:201], 1.0 op_sel_hi:[1,0]
	v_pk_fma_f32 v[190:191], v[78:79], v[6:7], v[190:191]
	v_pk_mul_f32 v[192:193], v[192:193], v[204:205]
	v_rcp_f32_e32 v200, v194
	v_rcp_f32_e32 v201, v195
	v_pk_fma_f32 v[190:191], v[150:151], v[2:3], v[190:191]
	v_pk_fma_f32 v[194:195], v[78:79], v[26:27], v[30:31]
	v_pk_mul_f32 v[186:187], v[186:187], v[200:201]
	v_pk_fma_f32 v[194:195], v[150:151], v[6:7], v[194:195]
	v_pk_mul_f32 v[178:179], v[178:179], v[186:187]
	v_pk_fma_f32 v[186:187], v[138:139], v[2:3], v[194:195]
	v_pk_fma_f32 v[194:195], v[104:105], v[28:29], v[32:33]
	v_pk_fma_f32 v[200:201], v[106:107], v[18:19], v[22:23]
	v_pk_fma_f32 v[204:205], v[82:83], v[18:19], v[22:23]
	v_pk_fma_f32 v[206:207], v[66:67], v[18:19], v[22:23]
	v_pk_fma_f32 v[200:201], v[82:83], v[14:15], v[200:201]
	v_pk_fma_f32 v[204:205], v[66:67], v[14:15], v[204:205]
	v_pk_fma_f32 v[194:195], v[80:81], v[8:9], v[194:195]
	v_pk_fma_f32 v[66:67], v[66:67], v[10:11], v[200:201]
	v_pk_fma_f32 v[200:201], v[54:55], v[10:11], v[204:205]
	v_pk_fma_f32 v[204:205], v[54:55], v[14:15], v[206:207]
	v_pk_mul_f32 v[206:207], v[66:67], s[82:83] op_sel_hi:[1,0]
	v_pk_fma_f32 v[54:55], v[54:55], v[18:19], v[22:23]
	v_fmac_f32_dpp v204, v106, v10 row_shr:1 row_mask:0xf bank_mask:0xf bound_ctrl:1
	v_fmac_f32_dpp v205, v107, v11 row_shr:1 row_mask:0xf bank_mask:0xf bound_ctrl:1
	v_pk_fma_f32 v[194:195], v[152:153], v[4:5], v[194:195]
	v_fmac_f32_dpp v54, v106, v14 row_shr:1 row_mask:0xf bank_mask:0xf bound_ctrl:1
	v_fmac_f32_dpp v55, v107, v15 row_shr:1 row_mask:0xf bank_mask:0xf bound_ctrl:1
	v_exp_f32_e32 v106, v206
	v_exp_f32_e32 v107, v207
	v_pk_fma_f32 v[206:207], v[80:81], v[28:29], v[32:33]
	v_pk_mul_f32 v[182:183], v[198:199], v[182:183]
	v_pk_mul_f32 v[198:199], v[200:201], s[82:83] op_sel_hi:[1,0]
	v_pk_add_f32 v[106:107], v[106:107], 1.0 op_sel_hi:[1,0]
	v_pk_fma_f32 v[206:207], v[152:153], v[8:9], v[206:207]
	v_pk_mul_f32 v[170:171], v[202:203], v[170:171]
	v_rcp_f32_e32 v202, v106
	v_rcp_f32_e32 v203, v107
	v_exp_f32_e32 v106, v198
	v_exp_f32_e32 v107, v199
	v_pk_fma_f32 v[198:199], v[140:141], v[4:5], v[206:207]
	v_pk_mul_f32 v[66:67], v[66:67], v[202:203]
	v_pk_fma_f32 v[202:203], v[152:153], v[28:29], v[32:33]
	v_pk_add_f32 v[106:107], v[106:107], 1.0 op_sel_hi:[1,0]
	v_pk_mul_f32 v[66:67], v[190:191], v[66:67]
	v_pk_fma_f32 v[190:191], v[150:151], v[26:27], v[30:31]
	v_rcp_f32_e32 v206, v106
	v_rcp_f32_e32 v207, v107
	v_pk_mul_f32 v[106:107], v[204:205], s[82:83] op_sel_hi:[1,0]
	v_pk_fma_f32 v[190:191], v[138:139], v[6:7], v[190:191]
	v_pk_fma_f32 v[202:203], v[140:141], v[8:9], v[202:203]
	v_pk_mul_f32 v[200:201], v[200:201], v[206:207]
	v_exp_f32_e32 v206, v106
	v_exp_f32_e32 v207, v107
	v_pk_mul_f32 v[106:107], v[186:187], v[200:201]
	v_fmac_f32_dpp v190, v102, v2 row_shr:1 row_mask:0xf bank_mask:0xf bound_ctrl:1
	v_fmac_f32_dpp v191, v103, v3 row_shr:1 row_mask:0xf bank_mask:0xf bound_ctrl:1
	v_pk_mul_f32 v[186:187], v[196:197], v[192:193]
	v_pk_add_f32 v[192:193], v[206:207], 1.0 op_sel_hi:[1,0]
	v_mov_b32_e32 v0, v158
	v_fmac_f32_dpp v54, v82, v10 row_shr:1 row_mask:0xf bank_mask:0xf bound_ctrl:1
	v_fmac_f32_dpp v55, v83, v11 row_shr:1 row_mask:0xf bank_mask:0xf bound_ctrl:1
	v_rcp_f32_e32 v82, v192
	v_rcp_f32_e32 v83, v193
	v_pk_mul_f32 v[192:193], v[54:55], s[82:83] op_sel_hi:[1,0]
	v_pk_fma_f32 v[196:197], v[138:139], v[26:27], v[30:31]
	v_pk_mul_f32 v[82:83], v[204:205], v[82:83]
	v_exp_f32_e32 v200, v192
	v_exp_f32_e32 v201, v193
	v_pk_mul_f32 v[82:83], v[190:191], v[82:83]
	v_fmac_f32_dpp v196, v102, v6 row_shr:1 row_mask:0xf bank_mask:0xf bound_ctrl:1
	v_fmac_f32_dpp v197, v103, v7 row_shr:1 row_mask:0xf bank_mask:0xf bound_ctrl:1
	s_nop 0
	v_fmac_f32_dpp v196, v78, v2 row_shr:1 row_mask:0xf bank_mask:0xf bound_ctrl:1
	v_fmac_f32_dpp v197, v79, v3 row_shr:1 row_mask:0xf bank_mask:0xf bound_ctrl:1
	v_pk_add_f32 v[78:79], v[200:201], 1.0 op_sel_hi:[1,0]
	v_pk_fma_f32 v[102:103], v[84:85], v[20:21], v[24:25]
	v_rcp_f32_e32 v190, v78
	v_rcp_f32_e32 v191, v79
	v_pk_fma_f32 v[78:79], v[68:69], v[16:17], v[102:103]
	v_pk_mul_f32 v[54:55], v[54:55], v[190:191]
	v_pk_fma_f32 v[78:79], v[56:57], v[12:13], v[78:79]
	v_pk_mul_f32 v[54:55], v[196:197], v[54:55]
	v_pk_fma_f32 v[102:103], v[140:141], v[28:29], v[32:33]
	v_pk_mul_f32 v[190:191], v[78:79], s[82:83] op_sel_hi:[1,0]
	v_pk_fma_f32 v[192:193], v[108:109], v[20:21], v[24:25]
	v_fmac_f32_dpp v202, v104, v4 row_shr:1 row_mask:0xf bank_mask:0xf bound_ctrl:1
	v_exp_f32_e32 v196, v190
	v_exp_f32_e32 v197, v191
	v_pk_fma_f32 v[190:191], v[84:85], v[16:17], v[192:193]
	v_fmac_f32_dpp v203, v105, v5 row_shr:1 row_mask:0xf bank_mask:0xf bound_ctrl:1
	v_fmac_f32_dpp v102, v104, v8 row_shr:1 row_mask:0xf bank_mask:0xf bound_ctrl:1
	v_fmac_f32_dpp v103, v105, v9 row_shr:1 row_mask:0xf bank_mask:0xf bound_ctrl:1
	v_pk_fma_f32 v[190:191], v[68:69], v[12:13], v[190:191]
	v_fmac_f32_dpp v102, v80, v4 row_shr:1 row_mask:0xf bank_mask:0xf bound_ctrl:1
	v_fmac_f32_dpp v103, v81, v5 row_shr:1 row_mask:0xf bank_mask:0xf bound_ctrl:1
	v_pk_add_f32 v[192:193], v[196:197], 1.0 op_sel_hi:[1,0]
	v_pk_mul_f32 v[196:197], v[190:191], s[82:83] op_sel_hi:[1,0]
	v_pk_fma_f32 v[200:201], v[68:69], v[20:21], v[24:25]
	v_rcp_f32_e32 v204, v192
	v_exp_f32_e32 v206, v196
	v_exp_f32_e32 v207, v197
	v_rcp_f32_e32 v205, v193
	v_pk_fma_f32 v[192:193], v[56:57], v[16:17], v[200:201]
	v_pk_fma_f32 v[56:57], v[56:57], v[20:21], v[24:25]
	v_pk_add_f32 v[196:197], v[206:207], 1.0 op_sel_hi:[1,0]
	v_pk_mul_f32 v[78:79], v[78:79], v[204:205]
	v_fmac_f32_dpp v192, v108, v12 row_shr:1 row_mask:0xf bank_mask:0xf bound_ctrl:1
	v_rcp_f32_e32 v200, v196
	v_rcp_f32_e32 v201, v197
	v_pk_mul_f32 v[78:79], v[198:199], v[78:79]
	v_fmac_f32_dpp v193, v109, v13 row_shr:1 row_mask:0xf bank_mask:0xf bound_ctrl:1
	v_fmac_f32_dpp v56, v108, v16 row_shr:1 row_mask:0xf bank_mask:0xf bound_ctrl:1
	v_fmac_f32_dpp v57, v109, v17 row_shr:1 row_mask:0xf bank_mask:0xf bound_ctrl:1
	v_pk_mul_f32 v[190:191], v[190:191], v[200:201]
	v_pk_mul_f32 v[196:197], v[192:193], s[82:83] op_sel_hi:[1,0]
	v_fmac_f32_dpp v56, v84, v12 row_shr:1 row_mask:0xf bank_mask:0xf bound_ctrl:1
	v_fmac_f32_dpp v57, v85, v13 row_shr:1 row_mask:0xf bank_mask:0xf bound_ctrl:1
	v_mov_b32_e32 v158, v182
	v_exp_f32_e32 v198, v196
	v_exp_f32_e32 v199, v197
	v_pk_mul_f32 v[196:197], v[56:57], s[82:83] op_sel_hi:[1,0]
	v_mov_b32_e32 v170, v170
	v_mov_b32_e32 v182, v187
	v_mov_b32_e32 v178, v178
	v_exp_f32_e32 v200, v196
	v_pk_add_f32 v[198:199], v[198:199], 1.0 op_sel_hi:[1,0]
	v_exp_f32_e32 v201, v197
	v_rcp_f32_e32 v196, v198
	v_rcp_f32_e32 v197, v199
	v_pk_add_f32 v[198:199], v[200:201], 1.0 op_sel_hi:[1,0]
	v_mov_b32_e32 v82, v82
	v_mov_b32_e32 v55, v55
	v_pk_mul_f32 v[192:193], v[192:193], v[196:197]
	v_rcp_f32_e32 v196, v198
	v_rcp_f32_e32 v197, v199
	v_pk_mul_f32 v[190:191], v[194:195], v[190:191]
	v_mov_b32_e32 v78, v78
	v_pk_mul_f32 v[56:57], v[56:57], v[196:197]
	v_pk_mul_f32 v[56:57], v[102:103], v[56:57]
	v_pk_mul_f32 v[102:103], v[202:203], v[192:193]
	v_mbcnt_lo_u32_b32 v187, -1, s0
	v_mov_b64_e32 v[192:193], s[12:13]
	v_cvt_pk_bf16_f32 v196, v154, v155
	v_mbcnt_hi_u32_b32 v187, -1, v187
	v_cvt_pk_bf16_f32 v197, v178, v179
	v_cvt_pk_bf16_f32 v198, v54, v55
	v_and_b32_e32 v54, 15, v187
	v_ashrrev_i32_e32 v55, 1, v187
	v_cvt_pk_bf16_f32 v199, v56, v57
	v_cmp_ne_u32_e64 s[98:99], 0, v54
	s_nop 3
	v_and_b32_e32 v55, -8, v55
	v_lshl_or_b32 v54, v54, 2, s21
	v_cvt_pk_bf16_f32 v200, v0, v159
	v_add_u32_e32 v56, s19, v55
	v_or_b32_e32 v0, 1, v54
	v_mad_i64_i32 v[154:155], s[2:3], v54, s94, v[192:193]
	v_ashrrev_i32_e32 v57, 31, v56
	v_mad_i64_i32 v[178:179], s[2:3], v0, s94, v[192:193]
	v_cvt_pk_bf16_f32 v201, v186, v182
	v_lshlrev_b64 v[56:57], 1, v[56:57]
	v_cvt_pk_bf16_f32 v202, v82, v83
	v_cvt_pk_bf16_f32 v203, v102, v103
	v_lshl_add_u64 v[82:83], v[154:155], 0, v[56:57]
	v_lshl_add_u64 v[102:103], v[178:179], 0, v[56:57]
	v_or_b32_e32 v0, 2, v54
	s_mov_b64 exec, s[98:99]
	global_store_dwordx4 v[82:83], v[196:199], off
	s_mov_b64 exec, -1
	s_mov_b64 exec, s[98:99]
	global_store_dwordx4 v[102:103], v[200:203], off
	s_mov_b64 exec, -1
	v_mov_b64_e32 v[154:155], s[12:13]
	v_cvt_pk_bf16_f32 v192, v48, v49
	v_cvt_pk_bf16_f32 v193, v170, v171
	v_mad_i64_i32 v[48:49], s[0:1], v0, s94, v[154:155]
	v_cvt_pk_bf16_f32 v194, v106, v107
	v_cvt_pk_bf16_f32 v195, v78, v79
	v_lshl_add_u64 v[48:49], v[48:49], 0, v[56:57]
	v_or_b32_e32 v0, 3, v54
	v_cvt_pk_bf16_f32 v199, v190, v191
	global_store_dwordx4 v[48:49], v[192:195], off
	v_mad_i64_i32 v[78:79], s[0:1], v0, s94, v[154:155]
	v_cvt_pk_bf16_f32 v196, v46, v47
	v_cvt_pk_bf16_f32 v197, v158, v183
	v_cvt_pk_bf16_f32 v198, v66, v67
	v_lshl_add_u64 v[46:47], v[78:79], 0, v[56:57]
	global_store_dwordx4 v[46:47], v[196:199], off
	v_pk_fma_f32 v[48:49], v[142:143], v[98:99], v[146:147]
	v_pk_fma_f32 v[66:67], v[144:145], v[100:101], v[148:149]
	v_pk_fma_f32 v[78:79], v[162:163], v[90:91], v[166:167]
	v_pk_fma_f32 v[46:47], v[126:127], v[94:95], v[48:49]
	v_pk_fma_f32 v[48:49], v[128:129], v[96:97], v[66:67]
	v_pk_fma_f32 v[66:67], v[114:115], v[86:87], v[78:79]
	v_pk_fma_f32 v[46:47], v[122:123], v[118:119], v[46:47]
	v_pk_fma_f32 v[48:49], v[124:125], v[120:121], v[48:49]
	v_pk_fma_f32 v[66:67], v[110:111], v[174:175], v[66:67]
	v_pk_mul_f32 v[78:79], v[46:47], s[82:83] op_sel_hi:[1,0]
	v_pk_fma_f32 v[82:83], v[144:145], v[96:97], v[148:149]
	v_pk_fma_f32 v[102:103], v[142:143], v[94:95], v[146:147]
	v_exp_f32_e32 v106, v78
	v_exp_f32_e32 v107, v79
	v_pk_fma_f32 v[78:79], v[128:129], v[120:121], v[82:83]
	v_pk_fma_f32 v[82:83], v[126:127], v[118:119], v[102:103]
	v_pk_fma_f32 v[102:103], v[164:165], v[88:89], v[168:169]
	v_pk_add_f32 v[106:107], v[106:107], 1.0 op_sel_hi:[1,0]
	v_pk_fma_f32 v[78:79], v[124:125], v[136:137], v[78:79]
	v_pk_fma_f32 v[82:83], v[122:123], v[134:135], v[82:83]
	v_rcp_f32_e32 v154, v106
	v_rcp_f32_e32 v155, v107
	v_pk_mul_f32 v[106:107], v[82:83], s[82:83] op_sel_hi:[1,0]
	v_pk_fma_f32 v[102:103], v[116:117], v[176:177], v[102:103]
	v_pk_fma_f32 v[158:159], v[162:163], v[86:87], v[166:167]
	v_pk_mul_f32 v[46:47], v[46:47], v[154:155]
	v_exp_f32_e32 v154, v106
	v_exp_f32_e32 v155, v107
	v_pk_mul_f32 v[46:47], v[66:67], v[46:47]
	v_pk_fma_f32 v[66:67], v[112:113], v[132:133], v[102:103]
	v_pk_fma_f32 v[102:103], v[114:115], v[174:175], v[158:159]
	v_pk_add_f32 v[106:107], v[154:155], 1.0 op_sel_hi:[1,0]
	v_pk_fma_f32 v[118:119], v[142:143], v[118:119], v[146:147]
	v_pk_fma_f32 v[102:103], v[110:111], v[130:131], v[102:103]
	v_rcp_f32_e32 v154, v106
	v_rcp_f32_e32 v155, v107
	v_pk_fma_f32 v[106:107], v[126:127], v[134:135], v[118:119]
	v_pk_fma_f32 v[118:119], v[144:145], v[120:121], v[148:149]
	v_pk_fma_f32 v[120:121], v[164:165], v[176:177], v[168:169]
	v_pk_mul_f32 v[82:83], v[82:83], v[154:155]
	v_fmac_f32_dpp v106, v98, v122 row_shr:1 row_mask:0xf bank_mask:0xf bound_ctrl:1
	v_fmac_f32_dpp v107, v99, v123 row_shr:1 row_mask:0xf bank_mask:0xf bound_ctrl:1
	v_pk_fma_f32 v[118:119], v[128:129], v[136:137], v[118:119]
	v_pk_mul_f32 v[82:83], v[102:103], v[82:83]
	v_pk_mul_f32 v[102:103], v[106:107], s[82:83] op_sel_hi:[1,0]
	v_pk_fma_f32 v[154:155], v[162:163], v[174:175], v[166:167]
	v_pk_fma_f32 v[120:121], v[116:117], v[132:133], v[120:121]
	v_exp_f32_e32 v158, v102
	v_exp_f32_e32 v159, v103
	v_pk_fma_f32 v[102:103], v[114:115], v[130:131], v[154:155]
	v_pk_fma_f32 v[130:131], v[162:163], v[130:131], v[166:167]
	v_pk_fma_f32 v[134:135], v[142:143], v[134:135], v[146:147]
	v_pk_add_f32 v[142:143], v[158:159], 1.0 op_sel_hi:[1,0]
	v_fmac_f32_dpp v102, v90, v110 row_shr:1 row_mask:0xf bank_mask:0xf bound_ctrl:1
	v_fmac_f32_dpp v103, v91, v111 row_shr:1 row_mask:0xf bank_mask:0xf bound_ctrl:1
	v_fmac_f32_dpp v130, v90, v114 row_shr:1 row_mask:0xf bank_mask:0xf bound_ctrl:1
	v_rcp_f32_e32 v154, v142
	v_rcp_f32_e32 v155, v143
	v_fmac_f32_dpp v131, v91, v115 row_shr:1 row_mask:0xf bank_mask:0xf bound_ctrl:1
	v_fmac_f32_dpp v130, v86, v110 row_shr:1 row_mask:0xf bank_mask:0xf bound_ctrl:1
	v_fmac_f32_dpp v134, v98, v126 row_shr:1 row_mask:0xf bank_mask:0xf bound_ctrl:1
	v_fmac_f32_dpp v131, v87, v111 row_shr:1 row_mask:0xf bank_mask:0xf bound_ctrl:1
	v_fmac_f32_dpp v135, v99, v127 row_shr:1 row_mask:0xf bank_mask:0xf bound_ctrl:1
	v_pk_mul_f32 v[86:87], v[106:107], v[154:155]
	v_pk_fma_f32 v[90:91], v[164:165], v[132:133], v[168:169]
	v_fmac_f32_dpp v134, v94, v122 row_shr:1 row_mask:0xf bank_mask:0xf bound_ctrl:1
	v_pk_mul_f32 v[86:87], v[102:103], v[86:87]
	v_fmac_f32_dpp v135, v95, v123 row_shr:1 row_mask:0xf bank_mask:0xf bound_ctrl:1
	v_pk_fma_f32 v[94:95], v[144:145], v[136:137], v[148:149]
	v_pk_mul_f32 v[98:99], v[134:135], s[82:83] op_sel_hi:[1,0]
	v_pk_fma_f32 v[102:103], v[164:165], v[92:93], v[168:169]
	v_exp_f32_e32 v106, v98
	v_exp_f32_e32 v107, v99
	v_fmac_f32_dpp v118, v100, v124 row_shr:1 row_mask:0xf bank_mask:0xf bound_ctrl:1
	v_fmac_f32_dpp v119, v101, v125 row_shr:1 row_mask:0xf bank_mask:0xf bound_ctrl:1
	v_pk_add_f32 v[98:99], v[106:107], 1.0 op_sel_hi:[1,0]
	v_pk_fma_f32 v[102:103], v[116:117], v[88:89], v[102:103]
	v_rcp_f32_e32 v106, v98
	v_rcp_f32_e32 v107, v99
	s_nop 0
	v_pk_mul_f32 v[98:99], v[134:135], v[106:107]
	v_fmac_f32_dpp v94, v100, v128 row_shr:1 row_mask:0xf bank_mask:0xf bound_ctrl:1
	v_fmac_f32_dpp v95, v101, v129 row_shr:1 row_mask:0xf bank_mask:0xf bound_ctrl:1
	v_pk_mul_f32 v[98:99], v[130:131], v[98:99]
	v_fmac_f32_dpp v94, v96, v124 row_shr:1 row_mask:0xf bank_mask:0xf bound_ctrl:1
	v_fmac_f32_dpp v95, v97, v125 row_shr:1 row_mask:0xf bank_mask:0xf bound_ctrl:1
	v_pk_fma_f32 v[96:97], v[112:113], v[176:177], v[102:103]
	v_pk_mul_f32 v[100:101], v[94:95], s[82:83] op_sel_hi:[1,0]
	v_pk_mul_f32 v[102:103], v[48:49], s[82:83] op_sel_hi:[1,0]
	v_fmac_f32_dpp v90, v92, v116 row_shr:1 row_mask:0xf bank_mask:0xf bound_ctrl:1
	v_exp_f32_e32 v106, v100
	v_exp_f32_e32 v107, v101
	v_exp_f32_e32 v100, v102
	v_exp_f32_e32 v101, v103
	v_fmac_f32_dpp v91, v93, v117 row_shr:1 row_mask:0xf bank_mask:0xf bound_ctrl:1
	v_fmac_f32_dpp v120, v92, v112 row_shr:1 row_mask:0xf bank_mask:0xf bound_ctrl:1
	v_fmac_f32_dpp v121, v93, v113 row_shr:1 row_mask:0xf bank_mask:0xf bound_ctrl:1
	v_fmac_f32_dpp v90, v88, v112 row_shr:1 row_mask:0xf bank_mask:0xf bound_ctrl:1
	v_fmac_f32_dpp v91, v89, v113 row_shr:1 row_mask:0xf bank_mask:0xf bound_ctrl:1
	v_pk_add_f32 v[88:89], v[100:101], 1.0 op_sel_hi:[1,0]
	v_pk_mul_f32 v[92:93], v[78:79], s[82:83] op_sel_hi:[1,0]
	v_pk_mul_f32 v[100:101], v[118:119], s[82:83] op_sel_hi:[1,0]
	v_rcp_f32_e32 v102, v88
	v_rcp_f32_e32 v103, v89
	v_exp_f32_e32 v88, v92
	v_exp_f32_e32 v89, v93
	v_exp_f32_e32 v92, v100
	v_pk_mul_f32 v[48:49], v[48:49], v[102:103]
	v_exp_f32_e32 v93, v101
	v_pk_add_f32 v[88:89], v[88:89], 1.0 op_sel_hi:[1,0]
	v_pk_fma_f32 v[100:101], v[36:37], v[28:29], v[32:33]
	v_pk_add_f32 v[102:103], v[106:107], 1.0 op_sel_hi:[1,0]
	v_pk_add_f32 v[92:93], v[92:93], 1.0 op_sel_hi:[1,0]
	v_pk_fma_f32 v[100:101], v[40:41], v[8:9], v[100:101]
	v_rcp_f32_e32 v106, v102
	v_rcp_f32_e32 v110, v92
	v_rcp_f32_e32 v111, v93
	v_rcp_f32_e32 v107, v103
	v_pk_mul_f32 v[92:93], v[118:119], v[110:111]
	v_pk_mul_f32 v[94:95], v[94:95], v[106:107]
	v_rcp_f32_e32 v102, v88
	v_rcp_f32_e32 v103, v89
	v_pk_mul_f32 v[88:89], v[90:91], v[94:95]
	v_mov_b32_e32 v0, v82
	v_pk_fma_f32 v[90:91], v[34:35], v[26:27], v[30:31]
	v_pk_mul_f32 v[78:79], v[78:79], v[102:103]
	v_pk_fma_f32 v[94:95], v[42:43], v[18:19], v[22:23]
	v_pk_fma_f32 v[90:91], v[38:39], v[6:7], v[90:91]
	v_pk_fma_f32 v[102:103], v[38:39], v[26:27], v[30:31]
	v_pk_fma_f32 v[94:95], v[58:59], v[14:15], v[94:95]
	v_pk_fma_f32 v[90:91], v[74:75], v[2:3], v[90:91]
	v_pk_fma_f32 v[102:103], v[74:75], v[6:7], v[102:103]
	v_pk_fma_f32 v[94:95], v[50:51], v[10:11], v[94:95]
	v_pk_fma_f32 v[74:75], v[74:75], v[26:27], v[30:31]
	v_pk_fma_f32 v[102:103], v[62:63], v[2:3], v[102:103]
	v_pk_mul_f32 v[106:107], v[94:95], s[82:83] op_sel_hi:[1,0]
	v_pk_fma_f32 v[26:27], v[62:63], v[26:27], v[30:31]
	v_pk_fma_f32 v[30:31], v[62:63], v[6:7], v[74:75]
	v_exp_f32_e32 v62, v106
	v_exp_f32_e32 v63, v107
	v_fmac_f32_dpp v26, v34, v6 row_shr:1 row_mask:0xf bank_mask:0xf bound_ctrl:1
	v_fmac_f32_dpp v27, v35, v7 row_shr:1 row_mask:0xf bank_mask:0xf bound_ctrl:1
	v_fmac_f32_dpp v30, v34, v2 row_shr:1 row_mask:0xf bank_mask:0xf bound_ctrl:1
	v_fmac_f32_dpp v31, v35, v3 row_shr:1 row_mask:0xf bank_mask:0xf bound_ctrl:1
	v_fmac_f32_dpp v26, v38, v2 row_shr:1 row_mask:0xf bank_mask:0xf bound_ctrl:1
	v_pk_add_f32 v[6:7], v[62:63], 1.0 op_sel_hi:[1,0]
	v_fmac_f32_dpp v27, v39, v3 row_shr:1 row_mask:0xf bank_mask:0xf bound_ctrl:1
	v_pk_fma_f32 v[2:3], v[58:59], v[18:19], v[22:23]
	v_rcp_f32_e32 v34, v6
	v_rcp_f32_e32 v35, v7
	v_pk_fma_f32 v[6:7], v[76:77], v[4:5], v[100:101]
	v_pk_fma_f32 v[2:3], v[50:51], v[14:15], v[2:3]
	v_pk_fma_f32 v[38:39], v[40:41], v[28:29], v[32:33]
	v_pk_mul_f32 v[34:35], v[94:95], v[34:35]
	v_pk_fma_f32 v[2:3], v[70:71], v[10:11], v[2:3]
	v_pk_fma_f32 v[38:39], v[76:77], v[8:9], v[38:39]
	v_pk_mul_f32 v[34:35], v[90:91], v[34:35]
	v_pk_mul_f32 v[62:63], v[2:3], s[82:83] op_sel_hi:[1,0]
	v_pk_fma_f32 v[74:75], v[76:77], v[28:29], v[32:33]
	v_pk_fma_f32 v[38:39], v[64:65], v[4:5], v[38:39]
	v_exp_f32_e32 v76, v62
	v_exp_f32_e32 v77, v63
	v_pk_fma_f32 v[50:51], v[50:51], v[18:19], v[22:23]
	v_pk_fma_f32 v[18:19], v[70:71], v[18:19], v[22:23]
	v_pk_fma_f32 v[22:23], v[64:65], v[28:29], v[32:33]
	v_pk_add_f32 v[28:29], v[76:77], 1.0 op_sel_hi:[1,0]
	v_pk_fma_f32 v[32:33], v[70:71], v[14:15], v[50:51]
	v_fmac_f32_dpp v18, v42, v14 row_shr:1 row_mask:0xf bank_mask:0xf bound_ctrl:1
	v_rcp_f32_e32 v50, v28
	v_rcp_f32_e32 v51, v29
	v_fmac_f32_dpp v19, v43, v15 row_shr:1 row_mask:0xf bank_mask:0xf bound_ctrl:1
	v_fmac_f32_dpp v32, v42, v10 row_shr:1 row_mask:0xf bank_mask:0xf bound_ctrl:1
	v_fmac_f32_dpp v33, v43, v11 row_shr:1 row_mask:0xf bank_mask:0xf bound_ctrl:1
	v_fmac_f32_dpp v18, v58, v10 row_shr:1 row_mask:0xf bank_mask:0xf bound_ctrl:1
	v_fmac_f32_dpp v19, v59, v11 row_shr:1 row_mask:0xf bank_mask:0xf bound_ctrl:1
	v_pk_mul_f32 v[2:3], v[2:3], v[50:51]
	v_pk_mul_f32 v[10:11], v[18:19], s[82:83] op_sel_hi:[1,0]
	v_pk_mul_f32 v[14:15], v[32:33], s[82:83] op_sel_hi:[1,0]
	v_pk_mul_f32 v[2:3], v[102:103], v[2:3]
	v_exp_f32_e32 v28, v10
	v_exp_f32_e32 v29, v11
	v_exp_f32_e32 v10, v14
	v_exp_f32_e32 v11, v15
	v_pk_fma_f32 v[14:15], v[64:65], v[8:9], v[74:75]
	v_pk_add_f32 v[28:29], v[28:29], 1.0 op_sel_hi:[1,0]
	v_fmac_f32_dpp v22, v36, v8 row_shr:1 row_mask:0xf bank_mask:0xf bound_ctrl:1
	v_pk_add_f32 v[10:11], v[10:11], 1.0 op_sel_hi:[1,0]
	v_rcp_f32_e32 v42, v28
	v_rcp_f32_e32 v43, v29
	v_rcp_f32_e32 v28, v10
	v_rcp_f32_e32 v29, v11
	v_fmac_f32_dpp v23, v37, v9 row_shr:1 row_mask:0xf bank_mask:0xf bound_ctrl:1
	v_pk_mul_f32 v[8:9], v[18:19], v[42:43]
	v_fmac_f32_dpp v14, v36, v4 row_shr:1 row_mask:0xf bank_mask:0xf bound_ctrl:1
	v_fmac_f32_dpp v15, v37, v5 row_shr:1 row_mask:0xf bank_mask:0xf bound_ctrl:1
	v_pk_mul_f32 v[10:11], v[32:33], v[28:29]
	v_pk_mul_f32 v[8:9], v[26:27], v[8:9]
	v_fmac_f32_dpp v22, v40, v4 row_shr:1 row_mask:0xf bank_mask:0xf bound_ctrl:1
	v_fmac_f32_dpp v23, v41, v5 row_shr:1 row_mask:0xf bank_mask:0xf bound_ctrl:1
	v_pk_mul_f32 v[4:5], v[30:31], v[10:11]
	v_mov_b32_e32 v55, v86
	v_mov_b32_e32 v82, v99
	v_pk_fma_f32 v[10:11], v[44:45], v[20:21], v[24:25]
	v_pk_fma_f32 v[18:19], v[60:61], v[20:21], v[24:25]
	v_pk_mul_f32 v[26:27], v[96:97], v[48:49]
	v_pk_fma_f32 v[10:11], v[60:61], v[16:17], v[10:11]
	v_pk_fma_f32 v[18:19], v[52:53], v[16:17], v[18:19]
	v_pk_mul_f32 v[28:29], v[66:67], v[78:79]
	v_pk_fma_f32 v[10:11], v[52:53], v[12:13], v[10:11]
	v_pk_fma_f32 v[18:19], v[72:73], v[12:13], v[18:19]
	v_pk_mul_f32 v[30:31], v[120:121], v[92:93]
	v_pk_mul_f32 v[32:33], v[10:11], s[82:83] op_sel_hi:[1,0]
	v_pk_mul_f32 v[36:37], v[18:19], s[82:83] op_sel_hi:[1,0]
	v_mov_b32_e32 v4, v4
	v_exp_f32_e32 v40, v32
	v_exp_f32_e32 v41, v33
	v_exp_f32_e32 v32, v36
	v_exp_f32_e32 v33, v37
	v_pk_fma_f32 v[36:37], v[52:53], v[20:21], v[24:25]
	v_pk_add_f32 v[40:41], v[40:41], 1.0 op_sel_hi:[1,0]
	v_pk_fma_f32 v[20:21], v[72:73], v[20:21], v[24:25]
	v_pk_add_f32 v[24:25], v[32:33], 1.0 op_sel_hi:[1,0]
	v_rcp_f32_e32 v32, v40
	v_rcp_f32_e32 v33, v41
	v_rcp_f32_e32 v40, v24
	v_rcp_f32_e32 v41, v25
	v_pk_fma_f32 v[24:25], v[72:73], v[16:17], v[36:37]
	v_pk_mul_f32 v[10:11], v[10:11], v[32:33]
	v_fmac_f32_dpp v20, v44, v16 row_shr:1 row_mask:0xf bank_mask:0xf bound_ctrl:1
	v_pk_mul_f32 v[18:19], v[18:19], v[40:41]
	v_pk_mul_f32 v[6:7], v[6:7], v[10:11]
	v_fmac_f32_dpp v21, v45, v17 row_shr:1 row_mask:0xf bank_mask:0xf bound_ctrl:1
	v_fmac_f32_dpp v24, v44, v12 row_shr:1 row_mask:0xf bank_mask:0xf bound_ctrl:1
	v_fmac_f32_dpp v25, v45, v13 row_shr:1 row_mask:0xf bank_mask:0xf bound_ctrl:1
	v_fmac_f32_dpp v20, v60, v12 row_shr:1 row_mask:0xf bank_mask:0xf bound_ctrl:1
	v_fmac_f32_dpp v21, v61, v13 row_shr:1 row_mask:0xf bank_mask:0xf bound_ctrl:1
	v_pk_mul_f32 v[10:11], v[24:25], s[82:83] op_sel_hi:[1,0]
	v_pk_mul_f32 v[12:13], v[20:21], s[82:83] op_sel_hi:[1,0]
	v_pk_mul_f32 v[16:17], v[38:39], v[18:19]
	v_exp_f32_e32 v18, v10
	v_exp_f32_e32 v32, v12
	v_exp_f32_e32 v33, v13
	v_exp_f32_e32 v19, v11
	v_mov_b32_e32 v6, v6
	v_mov_b32_e32 v17, v17
	v_pk_add_f32 v[10:11], v[32:33], 1.0 op_sel_hi:[1,0]
	v_pk_add_f32 v[12:13], v[18:19], 1.0 op_sel_hi:[1,0]
	v_rcp_f32_e32 v18, v10
	v_rcp_f32_e32 v19, v11
	v_rcp_f32_e32 v10, v12
	v_rcp_f32_e32 v11, v13
	v_pk_mul_f32 v[12:13], v[20:21], v[18:19]
	v_pk_mul_f32 v[10:11], v[24:25], v[10:11]
	v_pk_mul_f32 v[12:13], v[22:23], v[12:13]
	v_pk_mul_f32 v[10:11], v[14:15], v[10:11]
	v_mov_b32_e32 v12, v12
	v_add_u32_e32 v86, 0x80, v54
	v_cvt_pk_bf16_f32 v22, v8, v9
	v_mov_b64_e32 v[8:9], s[12:13]
	v_add_u32_e32 v99, 0x81, v54
	v_cvt_pk_bf16_f32 v20, v98, v82
	v_mad_i64_i32 v[14:15], s[2:3], v86, s94, v[8:9]
	v_mad_i64_i32 v[8:9], s[2:3], v99, s94, v[8:9]
	v_cvt_pk_bf16_f32 v21, v88, v89
	v_cvt_pk_bf16_f32 v23, v12, v13
	v_lshl_add_u64 v[12:13], v[14:15], 0, v[56:57]
	v_cvt_pk_bf16_f32 v36, v55, v87
	v_cvt_pk_bf16_f32 v37, v30, v31
	v_cvt_pk_bf16_f32 v38, v4, v5
	v_cvt_pk_bf16_f32 v39, v10, v11
	v_lshl_add_u64 v[4:5], v[8:9], 0, v[56:57]
	s_mov_b64 exec, s[98:99]
	global_store_dwordx4 v[12:13], v[20:23], off
	s_mov_b64 exec, -1
	v_add_u32_e32 v55, 0x82, v54
	s_mov_b64 exec, s[98:99]
	global_store_dwordx4 v[4:5], v[36:39], off
	s_mov_b64 exec, -1
	v_mov_b64_e32 v[8:9], s[12:13]
	v_add_u32_e32 v54, 0x83, v54
	v_cvt_pk_bf16_f32 v12, v0, v83
	v_mad_i64_i32 v[4:5], s[0:1], v55, s94, v[8:9]
	v_cvt_pk_bf16_f32 v13, v28, v29
	v_cvt_pk_bf16_f32 v14, v2, v3
	v_cvt_pk_bf16_f32 v15, v16, v17
	v_lshl_add_u64 v[2:3], v[4:5], 0, v[56:57]
	v_mad_i64_i32 v[4:5], s[0:1], v54, s94, v[8:9]
	v_cvt_pk_bf16_f32 v8, v46, v47
	global_store_dwordx4 v[2:3], v[12:15], off
	v_cvt_pk_bf16_f32 v9, v26, v27
	v_cvt_pk_bf16_f32 v10, v34, v35
	v_cvt_pk_bf16_f32 v11, v6, v7
	v_lshl_add_u64 v[2:3], v[4:5], 0, v[56:57]
	global_store_dwordx4 v[2:3], v[8:11], off
	s_andn2_b64 vcc, exec, s[4:5]
	s_mov_b64 s[0:1], -1
	s_cbranch_vccnz .LBB0_694
	s_andn2_b64 vcc, exec, s[8:9]
	s_cbranch_vccnz .LBB0_693
	s_barrier
	s_branch .LBB0_693
